# adds hand-written q/k RMS-norm+rotary epilogue (block-wise loads) on top of the balanced mapping; context detection via the unit's is-context flag
# speedup vs baseline: 1.0459x; 1.0119x over previous
.Lepi2_orig:
	s_cmp_gt_i32 s36, 4
	s_cbranch_scc1 .Lepi2_hip
	s_cmp_eq_u32 s36, 4
	s_cselect_b32 s58, s72, s70
	s_cselect_b32 s59, s73, s71
	s_lshl_b32 s12, s34, 8
	s_and_b32 s12, s12, 0x700
	v_lshrrev_b32_e32 v229, 1, v208
	v_and_b32_e32 v229, 0xffffffc0, v229
	v_and_b32_e32 v230, 31, v208
	v_or_b32_e32 v229, v229, v230
	v_mul_u32_u24_e32 v204, 0x210, v229
	v_lshlrev_b32_e32 v230, 2, v208
	v_and_b32_e32 v230, 0x100, v230
	v_add_u32_e32 v204, v204, v230
	v_lshrrev_b32_e32 v230, 2, v208
	v_and_b32_e32 v230, 8, v230
	v_add_u32_e32 v204, v204, v230
	v_lshlrev_b32_e32 v170, 1, v230
	v_lshlrev_b32_e32 v230, 2, v230
	v_add_u32_e32 v200, s12, v229
	v_and_b32_e32 v201, 63, v200
	v_lshrrev_b32_e32 v200, 6, v200
	v_lshl_add_u32 v200, v200, 8, v230
	v_lshl_add_u32 v201, v201, 8, v230
	v_add_u32_e32 v202, s12, v229
	v_add_u32_e32 v202, 32, v202
	v_and_b32_e32 v203, 63, v202
	v_lshrrev_b32_e32 v202, 6, v202
	v_lshl_add_u32 v202, v202, 8, v230
	v_lshl_add_u32 v203, v203, 8, v230
	v_lshrrev_b32_e32 v229, 5, v208
	v_and_b32_e32 v207, 31, v208
	v_lshlrev_b32_e32 v207, 4, v207
	v_mul_u32_u24_e32 v205, 0x210, v229
	v_add_u32_e32 v205, v205, v207
	v_add_u32_e32 v206, 0x10800, v205
	v_pk_mul_f32 v[180:181], v[112:113], v[112:113]
	v_pk_fma_f32 v[180:181], v[114:115], v[114:115], v[180:181]
	v_pk_fma_f32 v[180:181], v[116:117], v[116:117], v[180:181]
	v_pk_fma_f32 v[180:181], v[118:119], v[118:119], v[180:181]
	v_pk_fma_f32 v[180:181], v[120:121], v[120:121], v[180:181]
	v_pk_fma_f32 v[180:181], v[122:123], v[122:123], v[180:181]
	v_pk_fma_f32 v[180:181], v[124:125], v[124:125], v[180:181]
	v_pk_fma_f32 v[180:181], v[126:127], v[126:127], v[180:181]
	v_pk_fma_f32 v[180:181], v[80:81], v[80:81], v[180:181]
	v_pk_fma_f32 v[180:181], v[82:83], v[82:83], v[180:181]
	v_pk_fma_f32 v[180:181], v[84:85], v[84:85], v[180:181]
	v_pk_fma_f32 v[180:181], v[86:87], v[86:87], v[180:181]
	v_pk_fma_f32 v[180:181], v[88:89], v[88:89], v[180:181]
	v_pk_fma_f32 v[180:181], v[90:91], v[90:91], v[180:181]
	v_pk_fma_f32 v[180:181], v[92:93], v[92:93], v[180:181]
	v_pk_fma_f32 v[180:181], v[94:95], v[94:95], v[180:181]
	v_pk_fma_f32 v[180:181], v[96:97], v[96:97], v[180:181]
	v_pk_fma_f32 v[180:181], v[98:99], v[98:99], v[180:181]
	v_pk_fma_f32 v[180:181], v[100:101], v[100:101], v[180:181]
	v_pk_fma_f32 v[180:181], v[102:103], v[102:103], v[180:181]
	v_pk_fma_f32 v[180:181], v[104:105], v[104:105], v[180:181]
	v_pk_fma_f32 v[180:181], v[106:107], v[106:107], v[180:181]
	v_pk_fma_f32 v[180:181], v[108:109], v[108:109], v[180:181]
	v_pk_fma_f32 v[180:181], v[110:111], v[110:111], v[180:181]
	v_pk_fma_f32 v[180:181], v[64:65], v[64:65], v[180:181]
	v_pk_fma_f32 v[180:181], v[66:67], v[66:67], v[180:181]
	v_pk_fma_f32 v[180:181], v[68:69], v[68:69], v[180:181]
	v_pk_fma_f32 v[180:181], v[70:71], v[70:71], v[180:181]
	v_pk_fma_f32 v[180:181], v[72:73], v[72:73], v[180:181]
	v_pk_fma_f32 v[180:181], v[74:75], v[74:75], v[180:181]
	v_pk_fma_f32 v[180:181], v[76:77], v[76:77], v[180:181]
	v_pk_fma_f32 v[180:181], v[78:79], v[78:79], v[180:181]
	v_add_f32_e32 v180, v180, v181
	v_mov_b32_e32 v181, v180
	s_nop 1
	v_permlane32_swap_b32_e32 v180, v181
	s_nop 1
	v_add_f32_e32 v180, v180, v181
	v_mov_b32_e32 v181, 0x358637bd
	v_fmac_f32_e32 v181, 0x3c000000, v180
	v_rsq_f32_e32 v196, v181
	s_nop 0
	v_mov_b32_e32 v197, v196
	v_pk_mul_f32 v[180:181], v[48:49], v[48:49]
	v_pk_fma_f32 v[180:181], v[50:51], v[50:51], v[180:181]
	v_pk_fma_f32 v[180:181], v[52:53], v[52:53], v[180:181]
	v_pk_fma_f32 v[180:181], v[54:55], v[54:55], v[180:181]
	v_pk_fma_f32 v[180:181], v[56:57], v[56:57], v[180:181]
	v_pk_fma_f32 v[180:181], v[58:59], v[58:59], v[180:181]
	v_pk_fma_f32 v[180:181], v[60:61], v[60:61], v[180:181]
	v_pk_fma_f32 v[180:181], v[62:63], v[62:63], v[180:181]
	v_pk_fma_f32 v[180:181], v[16:17], v[16:17], v[180:181]
	v_pk_fma_f32 v[180:181], v[18:19], v[18:19], v[180:181]
	v_pk_fma_f32 v[180:181], v[20:21], v[20:21], v[180:181]
	v_pk_fma_f32 v[180:181], v[22:23], v[22:23], v[180:181]
	v_pk_fma_f32 v[180:181], v[24:25], v[24:25], v[180:181]
	v_pk_fma_f32 v[180:181], v[26:27], v[26:27], v[180:181]
	v_pk_fma_f32 v[180:181], v[28:29], v[28:29], v[180:181]
	v_pk_fma_f32 v[180:181], v[30:31], v[30:31], v[180:181]
	v_pk_fma_f32 v[180:181], v[32:33], v[32:33], v[180:181]
	v_pk_fma_f32 v[180:181], v[34:35], v[34:35], v[180:181]
	v_pk_fma_f32 v[180:181], v[36:37], v[36:37], v[180:181]
	v_pk_fma_f32 v[180:181], v[38:39], v[38:39], v[180:181]
	v_pk_fma_f32 v[180:181], v[40:41], v[40:41], v[180:181]
	v_pk_fma_f32 v[180:181], v[42:43], v[42:43], v[180:181]
	v_pk_fma_f32 v[180:181], v[44:45], v[44:45], v[180:181]
	v_pk_fma_f32 v[180:181], v[46:47], v[46:47], v[180:181]
	v_pk_fma_f32 v[180:181], v[0:1], v[0:1], v[180:181]
	v_pk_fma_f32 v[180:181], v[2:3], v[2:3], v[180:181]
	v_pk_fma_f32 v[180:181], v[4:5], v[4:5], v[180:181]
	v_pk_fma_f32 v[180:181], v[6:7], v[6:7], v[180:181]
	v_pk_fma_f32 v[180:181], v[8:9], v[8:9], v[180:181]
	v_pk_fma_f32 v[180:181], v[10:11], v[10:11], v[180:181]
	v_pk_fma_f32 v[180:181], v[12:13], v[12:13], v[180:181]
	v_pk_fma_f32 v[180:181], v[14:15], v[14:15], v[180:181]
	v_add_f32_e32 v180, v180, v181
	v_mov_b32_e32 v181, v180
	s_nop 1
	v_permlane32_swap_b32_e32 v180, v181
	s_nop 1
	v_add_f32_e32 v180, v180, v181
	v_mov_b32_e32 v181, 0x358637bd
	v_fmac_f32_e32 v181, 0x3c000000, v180
	v_rsq_f32_e32 v198, v181
	s_nop 0
	v_mov_b32_e32 v199, v198
	s_cmp_lg_u32 s26, 0
	s_cbranch_scc1 .Lqk2_ctx
	global_load_dwordx4 v[128:131], v170, s[58:59] offset:0
	global_load_dwordx4 v[132:135], v170, s[58:59] offset:256
	global_load_dwordx4 v[144:147], v200, s[8:9] offset:0
	global_load_dwordx4 v[148:151], v200, s[8:9] offset:16
	global_load_dwordx4 v[152:155], v202, s[8:9] offset:0
	global_load_dwordx4 v[156:159], v202, s[8:9] offset:16
	global_load_dwordx4 v[136:139], v170, s[58:59] offset:32
	global_load_dwordx4 v[140:143], v170, s[58:59] offset:288
	global_load_dwordx4 v[160:163], v200, s[8:9] offset:64
	global_load_dwordx4 v[164:167], v200, s[8:9] offset:80
	global_load_dwordx4 v[172:175], v202, s[8:9] offset:64
	global_load_dwordx4 v[176:179], v202, s[8:9] offset:80
	s_waitcnt vmcnt(6)
	v_pk_mul_f32 v[180:181], v[112:113], v[196:197]
	v_pk_mul_f32 v[184:185], v[96:97], v[196:197]
	v_pk_mul_f32 v[182:183], v[114:115], v[196:197]
	v_pk_mul_f32 v[186:187], v[98:99], v[196:197]
	v_pk_mul_f32 v[180:181], v[180:181], v[128:129]
	v_pk_mul_f32 v[184:185], v[184:185], v[132:133]
	v_pk_mul_f32 v[182:183], v[182:183], v[130:131]
	v_pk_mul_f32 v[186:187], v[186:187], v[134:135]
	v_mul_f32_e32 v188, v184, v145
	v_mul_f32_e32 v192, v180, v145
	v_mul_f32_e32 v189, v185, v147
	v_mul_f32_e32 v193, v181, v147
	v_mul_f32_e32 v190, v186, v149
	v_mul_f32_e32 v194, v182, v149
	v_mul_f32_e32 v191, v187, v151
	v_mul_f32_e32 v195, v183, v151
	v_fma_f32 v188, v180, v144, -v188
	v_fma_f32 v192, v184, v144, v192
	v_fma_f32 v189, v181, v146, -v189
	v_fma_f32 v193, v185, v146, v193
	v_fma_f32 v190, v182, v148, -v190
	v_fma_f32 v194, v186, v148, v194
	v_fma_f32 v191, v183, v150, -v191
	v_fma_f32 v195, v187, v150, v195
	v_cvt_pk_bf16_f32 v188, v188, v189
	v_cvt_pk_bf16_f32 v189, v190, v191
	v_cvt_pk_bf16_f32 v190, v192, v193
	v_cvt_pk_bf16_f32 v191, v194, v195
	ds_write_b64 v204, v[188:189] offset:0
	ds_write_b64 v204, v[190:191] offset:128
	v_pk_mul_f32 v[180:181], v[48:49], v[198:199]
	v_pk_mul_f32 v[184:185], v[32:33], v[198:199]
	v_pk_mul_f32 v[182:183], v[50:51], v[198:199]
	v_pk_mul_f32 v[186:187], v[34:35], v[198:199]
	v_pk_mul_f32 v[180:181], v[180:181], v[128:129]
	v_pk_mul_f32 v[184:185], v[184:185], v[132:133]
	v_pk_mul_f32 v[182:183], v[182:183], v[130:131]
	v_pk_mul_f32 v[186:187], v[186:187], v[134:135]
	v_mul_f32_e32 v188, v184, v153
	v_mul_f32_e32 v192, v180, v153
	v_mul_f32_e32 v189, v185, v155
	v_mul_f32_e32 v193, v181, v155
	v_mul_f32_e32 v190, v186, v157
	v_mul_f32_e32 v194, v182, v157
	v_mul_f32_e32 v191, v187, v159
	v_mul_f32_e32 v195, v183, v159
	v_fma_f32 v188, v180, v152, -v188
	v_fma_f32 v192, v184, v152, v192
	v_fma_f32 v189, v181, v154, -v189
	v_fma_f32 v193, v185, v154, v193
	v_fma_f32 v190, v182, v156, -v190
	v_fma_f32 v194, v186, v156, v194
	v_fma_f32 v191, v183, v158, -v191
	v_fma_f32 v195, v187, v158, v195
	v_cvt_pk_bf16_f32 v188, v188, v189
	v_cvt_pk_bf16_f32 v189, v190, v191
	v_cvt_pk_bf16_f32 v190, v192, v193
	v_cvt_pk_bf16_f32 v191, v194, v195
	ds_write_b64 v204, v[188:189] offset:16896
	ds_write_b64 v204, v[190:191] offset:17024
	global_load_dwordx4 v[128:131], v170, s[58:59] offset:64
	global_load_dwordx4 v[132:135], v170, s[58:59] offset:320
	global_load_dwordx4 v[144:147], v200, s[8:9] offset:128
	global_load_dwordx4 v[148:151], v200, s[8:9] offset:144
	global_load_dwordx4 v[152:155], v202, s[8:9] offset:128
	global_load_dwordx4 v[156:159], v202, s[8:9] offset:144
	s_waitcnt vmcnt(6)
	v_pk_mul_f32 v[180:181], v[116:117], v[196:197]
	v_pk_mul_f32 v[184:185], v[100:101], v[196:197]
	v_pk_mul_f32 v[182:183], v[118:119], v[196:197]
	v_pk_mul_f32 v[186:187], v[102:103], v[196:197]
	v_pk_mul_f32 v[180:181], v[180:181], v[136:137]
	v_pk_mul_f32 v[184:185], v[184:185], v[140:141]
	v_pk_mul_f32 v[182:183], v[182:183], v[138:139]
	v_pk_mul_f32 v[186:187], v[186:187], v[142:143]
	v_mul_f32_e32 v188, v184, v161
	v_mul_f32_e32 v192, v180, v161
	v_mul_f32_e32 v189, v185, v163
	v_mul_f32_e32 v193, v181, v163
	v_mul_f32_e32 v190, v186, v165
	v_mul_f32_e32 v194, v182, v165
	v_mul_f32_e32 v191, v187, v167
	v_mul_f32_e32 v195, v183, v167
	v_fma_f32 v188, v180, v160, -v188
	v_fma_f32 v192, v184, v160, v192
	v_fma_f32 v189, v181, v162, -v189
	v_fma_f32 v193, v185, v162, v193
	v_fma_f32 v190, v182, v164, -v190
	v_fma_f32 v194, v186, v164, v194
	v_fma_f32 v191, v183, v166, -v191
	v_fma_f32 v195, v187, v166, v195
	v_cvt_pk_bf16_f32 v188, v188, v189
	v_cvt_pk_bf16_f32 v189, v190, v191
	v_cvt_pk_bf16_f32 v190, v192, v193
	v_cvt_pk_bf16_f32 v191, v194, v195
	ds_write_b64 v204, v[188:189] offset:16
	ds_write_b64 v204, v[190:191] offset:144
	v_pk_mul_f32 v[180:181], v[52:53], v[198:199]
	v_pk_mul_f32 v[184:185], v[36:37], v[198:199]
	v_pk_mul_f32 v[182:183], v[54:55], v[198:199]
	v_pk_mul_f32 v[186:187], v[38:39], v[198:199]
	v_pk_mul_f32 v[180:181], v[180:181], v[136:137]
	v_pk_mul_f32 v[184:185], v[184:185], v[140:141]
	v_pk_mul_f32 v[182:183], v[182:183], v[138:139]
	v_pk_mul_f32 v[186:187], v[186:187], v[142:143]
	v_mul_f32_e32 v188, v184, v173
	v_mul_f32_e32 v192, v180, v173
	v_mul_f32_e32 v189, v185, v175
	v_mul_f32_e32 v193, v181, v175
	v_mul_f32_e32 v190, v186, v177
	v_mul_f32_e32 v194, v182, v177
	v_mul_f32_e32 v191, v187, v179
	v_mul_f32_e32 v195, v183, v179
	v_fma_f32 v188, v180, v172, -v188
	v_fma_f32 v192, v184, v172, v192
	v_fma_f32 v189, v181, v174, -v189
	v_fma_f32 v193, v185, v174, v193
	v_fma_f32 v190, v182, v176, -v190
	v_fma_f32 v194, v186, v176, v194
	v_fma_f32 v191, v183, v178, -v191
	v_fma_f32 v195, v187, v178, v195
	v_cvt_pk_bf16_f32 v188, v188, v189
	v_cvt_pk_bf16_f32 v189, v190, v191
	v_cvt_pk_bf16_f32 v190, v192, v193
	v_cvt_pk_bf16_f32 v191, v194, v195
	ds_write_b64 v204, v[188:189] offset:16912
	ds_write_b64 v204, v[190:191] offset:17040
	global_load_dwordx4 v[136:139], v170, s[58:59] offset:96
	global_load_dwordx4 v[140:143], v170, s[58:59] offset:352
	global_load_dwordx4 v[160:163], v200, s[8:9] offset:192
	global_load_dwordx4 v[164:167], v200, s[8:9] offset:208
	global_load_dwordx4 v[172:175], v202, s[8:9] offset:192
	global_load_dwordx4 v[176:179], v202, s[8:9] offset:208
	s_waitcnt vmcnt(6)
	v_pk_mul_f32 v[180:181], v[120:121], v[196:197]
	v_pk_mul_f32 v[184:185], v[104:105], v[196:197]
	v_pk_mul_f32 v[182:183], v[122:123], v[196:197]
	v_pk_mul_f32 v[186:187], v[106:107], v[196:197]
	v_pk_mul_f32 v[180:181], v[180:181], v[128:129]
	v_pk_mul_f32 v[184:185], v[184:185], v[132:133]
	v_pk_mul_f32 v[182:183], v[182:183], v[130:131]
	v_pk_mul_f32 v[186:187], v[186:187], v[134:135]
	v_mul_f32_e32 v188, v184, v145
	v_mul_f32_e32 v192, v180, v145
	v_mul_f32_e32 v189, v185, v147
	v_mul_f32_e32 v193, v181, v147
	v_mul_f32_e32 v190, v186, v149
	v_mul_f32_e32 v194, v182, v149
	v_mul_f32_e32 v191, v187, v151
	v_mul_f32_e32 v195, v183, v151
	v_fma_f32 v188, v180, v144, -v188
	v_fma_f32 v192, v184, v144, v192
	v_fma_f32 v189, v181, v146, -v189
	v_fma_f32 v193, v185, v146, v193
	v_fma_f32 v190, v182, v148, -v190
	v_fma_f32 v194, v186, v148, v194
	v_fma_f32 v191, v183, v150, -v191
	v_fma_f32 v195, v187, v150, v195
	v_cvt_pk_bf16_f32 v188, v188, v189
	v_cvt_pk_bf16_f32 v189, v190, v191
	v_cvt_pk_bf16_f32 v190, v192, v193
	v_cvt_pk_bf16_f32 v191, v194, v195
	ds_write_b64 v204, v[188:189] offset:32
	ds_write_b64 v204, v[190:191] offset:160
	v_pk_mul_f32 v[180:181], v[56:57], v[198:199]
	v_pk_mul_f32 v[184:185], v[40:41], v[198:199]
	v_pk_mul_f32 v[182:183], v[58:59], v[198:199]
	v_pk_mul_f32 v[186:187], v[42:43], v[198:199]
	v_pk_mul_f32 v[180:181], v[180:181], v[128:129]
	v_pk_mul_f32 v[184:185], v[184:185], v[132:133]
	v_pk_mul_f32 v[182:183], v[182:183], v[130:131]
	v_pk_mul_f32 v[186:187], v[186:187], v[134:135]
	v_mul_f32_e32 v188, v184, v153
	v_mul_f32_e32 v192, v180, v153
	v_mul_f32_e32 v189, v185, v155
	v_mul_f32_e32 v193, v181, v155
	v_mul_f32_e32 v190, v186, v157
	v_mul_f32_e32 v194, v182, v157
	v_mul_f32_e32 v191, v187, v159
	v_mul_f32_e32 v195, v183, v159
	v_fma_f32 v188, v180, v152, -v188
	v_fma_f32 v192, v184, v152, v192
	v_fma_f32 v189, v181, v154, -v189
	v_fma_f32 v193, v185, v154, v193
	v_fma_f32 v190, v182, v156, -v190
	v_fma_f32 v194, v186, v156, v194
	v_fma_f32 v191, v183, v158, -v191
	v_fma_f32 v195, v187, v158, v195
	v_cvt_pk_bf16_f32 v188, v188, v189
	v_cvt_pk_bf16_f32 v189, v190, v191
	v_cvt_pk_bf16_f32 v190, v192, v193
	v_cvt_pk_bf16_f32 v191, v194, v195
	ds_write_b64 v204, v[188:189] offset:16928
	ds_write_b64 v204, v[190:191] offset:17056
	global_load_dwordx4 v[128:131], v170, s[58:59] offset:128
	global_load_dwordx4 v[132:135], v170, s[58:59] offset:384
	global_load_dwordx4 v[144:147], v201, s[8:9] offset:0
	global_load_dwordx4 v[148:151], v201, s[8:9] offset:16
	global_load_dwordx4 v[152:155], v203, s[8:9] offset:0
	global_load_dwordx4 v[156:159], v203, s[8:9] offset:16
	s_waitcnt vmcnt(6)
	v_pk_mul_f32 v[180:181], v[124:125], v[196:197]
	v_pk_mul_f32 v[184:185], v[108:109], v[196:197]
	v_pk_mul_f32 v[182:183], v[126:127], v[196:197]
	v_pk_mul_f32 v[186:187], v[110:111], v[196:197]
	v_pk_mul_f32 v[180:181], v[180:181], v[136:137]
	v_pk_mul_f32 v[184:185], v[184:185], v[140:141]
	v_pk_mul_f32 v[182:183], v[182:183], v[138:139]
	v_pk_mul_f32 v[186:187], v[186:187], v[142:143]
	v_mul_f32_e32 v188, v184, v161
	v_mul_f32_e32 v192, v180, v161
	v_mul_f32_e32 v189, v185, v163
	v_mul_f32_e32 v193, v181, v163
	v_mul_f32_e32 v190, v186, v165
	v_mul_f32_e32 v194, v182, v165
	v_mul_f32_e32 v191, v187, v167
	v_mul_f32_e32 v195, v183, v167
	v_fma_f32 v188, v180, v160, -v188
	v_fma_f32 v192, v184, v160, v192
	v_fma_f32 v189, v181, v162, -v189
	v_fma_f32 v193, v185, v162, v193
	v_fma_f32 v190, v182, v164, -v190
	v_fma_f32 v194, v186, v164, v194
	v_fma_f32 v191, v183, v166, -v191
	v_fma_f32 v195, v187, v166, v195
	v_cvt_pk_bf16_f32 v188, v188, v189
	v_cvt_pk_bf16_f32 v189, v190, v191
	v_cvt_pk_bf16_f32 v190, v192, v193
	v_cvt_pk_bf16_f32 v191, v194, v195
	ds_write_b64 v204, v[188:189] offset:48
	ds_write_b64 v204, v[190:191] offset:176
	v_pk_mul_f32 v[180:181], v[60:61], v[198:199]
	v_pk_mul_f32 v[184:185], v[44:45], v[198:199]
	v_pk_mul_f32 v[182:183], v[62:63], v[198:199]
	v_pk_mul_f32 v[186:187], v[46:47], v[198:199]
	v_pk_mul_f32 v[180:181], v[180:181], v[136:137]
	v_pk_mul_f32 v[184:185], v[184:185], v[140:141]
	v_pk_mul_f32 v[182:183], v[182:183], v[138:139]
	v_pk_mul_f32 v[186:187], v[186:187], v[142:143]
	v_mul_f32_e32 v188, v184, v173
	v_mul_f32_e32 v192, v180, v173
	v_mul_f32_e32 v189, v185, v175
	v_mul_f32_e32 v193, v181, v175
	v_mul_f32_e32 v190, v186, v177
	v_mul_f32_e32 v194, v182, v177
	v_mul_f32_e32 v191, v187, v179
	v_mul_f32_e32 v195, v183, v179
	v_fma_f32 v188, v180, v172, -v188
	v_fma_f32 v192, v184, v172, v192
	v_fma_f32 v189, v181, v174, -v189
	v_fma_f32 v193, v185, v174, v193
	v_fma_f32 v190, v182, v176, -v190
	v_fma_f32 v194, v186, v176, v194
	v_fma_f32 v191, v183, v178, -v191
	v_fma_f32 v195, v187, v178, v195
	v_cvt_pk_bf16_f32 v188, v188, v189
	v_cvt_pk_bf16_f32 v189, v190, v191
	v_cvt_pk_bf16_f32 v190, v192, v193
	v_cvt_pk_bf16_f32 v191, v194, v195
	ds_write_b64 v204, v[188:189] offset:16944
	ds_write_b64 v204, v[190:191] offset:17072
	global_load_dwordx4 v[136:139], v170, s[58:59] offset:160
	global_load_dwordx4 v[140:143], v170, s[58:59] offset:416
	global_load_dwordx4 v[160:163], v201, s[8:9] offset:64
	global_load_dwordx4 v[164:167], v201, s[8:9] offset:80
	global_load_dwordx4 v[172:175], v203, s[8:9] offset:64
	global_load_dwordx4 v[176:179], v203, s[8:9] offset:80
	s_waitcnt vmcnt(6)
	v_pk_mul_f32 v[180:181], v[80:81], v[196:197]
	v_pk_mul_f32 v[184:185], v[64:65], v[196:197]
	v_pk_mul_f32 v[182:183], v[82:83], v[196:197]
	v_pk_mul_f32 v[186:187], v[66:67], v[196:197]
	v_pk_mul_f32 v[180:181], v[180:181], v[128:129]
	v_pk_mul_f32 v[184:185], v[184:185], v[132:133]
	v_pk_mul_f32 v[182:183], v[182:183], v[130:131]
	v_pk_mul_f32 v[186:187], v[186:187], v[134:135]
	v_mul_f32_e32 v188, v184, v145
	v_mul_f32_e32 v192, v180, v145
	v_mul_f32_e32 v189, v185, v147
	v_mul_f32_e32 v193, v181, v147
	v_mul_f32_e32 v190, v186, v149
	v_mul_f32_e32 v194, v182, v149
	v_mul_f32_e32 v191, v187, v151
	v_mul_f32_e32 v195, v183, v151
	v_fma_f32 v188, v180, v144, -v188
	v_fma_f32 v192, v184, v144, v192
	v_fma_f32 v189, v181, v146, -v189
	v_fma_f32 v193, v185, v146, v193
	v_fma_f32 v190, v182, v148, -v190
	v_fma_f32 v194, v186, v148, v194
	v_fma_f32 v191, v183, v150, -v191
	v_fma_f32 v195, v187, v150, v195
	v_cvt_pk_bf16_f32 v188, v188, v189
	v_cvt_pk_bf16_f32 v189, v190, v191
	v_cvt_pk_bf16_f32 v190, v192, v193
	v_cvt_pk_bf16_f32 v191, v194, v195
	ds_write_b64 v204, v[188:189] offset:64
	ds_write_b64 v204, v[190:191] offset:192
	v_pk_mul_f32 v[180:181], v[16:17], v[198:199]
	v_pk_mul_f32 v[184:185], v[0:1], v[198:199]
	v_pk_mul_f32 v[182:183], v[18:19], v[198:199]
	v_pk_mul_f32 v[186:187], v[2:3], v[198:199]
	v_pk_mul_f32 v[180:181], v[180:181], v[128:129]
	v_pk_mul_f32 v[184:185], v[184:185], v[132:133]
	v_pk_mul_f32 v[182:183], v[182:183], v[130:131]
	v_pk_mul_f32 v[186:187], v[186:187], v[134:135]
	v_mul_f32_e32 v188, v184, v153
	v_mul_f32_e32 v192, v180, v153
	v_mul_f32_e32 v189, v185, v155
	v_mul_f32_e32 v193, v181, v155
	v_mul_f32_e32 v190, v186, v157
	v_mul_f32_e32 v194, v182, v157
	v_mul_f32_e32 v191, v187, v159
	v_mul_f32_e32 v195, v183, v159
	v_fma_f32 v188, v180, v152, -v188
	v_fma_f32 v192, v184, v152, v192
	v_fma_f32 v189, v181, v154, -v189
	v_fma_f32 v193, v185, v154, v193
	v_fma_f32 v190, v182, v156, -v190
	v_fma_f32 v194, v186, v156, v194
	v_fma_f32 v191, v183, v158, -v191
	v_fma_f32 v195, v187, v158, v195
	v_cvt_pk_bf16_f32 v188, v188, v189
	v_cvt_pk_bf16_f32 v189, v190, v191
	v_cvt_pk_bf16_f32 v190, v192, v193
	v_cvt_pk_bf16_f32 v191, v194, v195
	ds_write_b64 v204, v[188:189] offset:16960
	ds_write_b64 v204, v[190:191] offset:17088
	global_load_dwordx4 v[128:131], v170, s[58:59] offset:192
	global_load_dwordx4 v[132:135], v170, s[58:59] offset:448
	global_load_dwordx4 v[144:147], v201, s[8:9] offset:128
	global_load_dwordx4 v[148:151], v201, s[8:9] offset:144
	global_load_dwordx4 v[152:155], v203, s[8:9] offset:128
	global_load_dwordx4 v[156:159], v203, s[8:9] offset:144
	s_waitcnt vmcnt(6)
	v_pk_mul_f32 v[180:181], v[84:85], v[196:197]
	v_pk_mul_f32 v[184:185], v[68:69], v[196:197]
	v_pk_mul_f32 v[182:183], v[86:87], v[196:197]
	v_pk_mul_f32 v[186:187], v[70:71], v[196:197]
	v_pk_mul_f32 v[180:181], v[180:181], v[136:137]
	v_pk_mul_f32 v[184:185], v[184:185], v[140:141]
	v_pk_mul_f32 v[182:183], v[182:183], v[138:139]
	v_pk_mul_f32 v[186:187], v[186:187], v[142:143]
	v_mul_f32_e32 v188, v184, v161
	v_mul_f32_e32 v192, v180, v161
	v_mul_f32_e32 v189, v185, v163
	v_mul_f32_e32 v193, v181, v163
	v_mul_f32_e32 v190, v186, v165
	v_mul_f32_e32 v194, v182, v165
	v_mul_f32_e32 v191, v187, v167
	v_mul_f32_e32 v195, v183, v167
	v_fma_f32 v188, v180, v160, -v188
	v_fma_f32 v192, v184, v160, v192
	v_fma_f32 v189, v181, v162, -v189
	v_fma_f32 v193, v185, v162, v193
	v_fma_f32 v190, v182, v164, -v190
	v_fma_f32 v194, v186, v164, v194
	v_fma_f32 v191, v183, v166, -v191
	v_fma_f32 v195, v187, v166, v195
	v_cvt_pk_bf16_f32 v188, v188, v189
	v_cvt_pk_bf16_f32 v189, v190, v191
	v_cvt_pk_bf16_f32 v190, v192, v193
	v_cvt_pk_bf16_f32 v191, v194, v195
	ds_write_b64 v204, v[188:189] offset:80
	ds_write_b64 v204, v[190:191] offset:208
	v_pk_mul_f32 v[180:181], v[20:21], v[198:199]
	v_pk_mul_f32 v[184:185], v[4:5], v[198:199]
	v_pk_mul_f32 v[182:183], v[22:23], v[198:199]
	v_pk_mul_f32 v[186:187], v[6:7], v[198:199]
	v_pk_mul_f32 v[180:181], v[180:181], v[136:137]
	v_pk_mul_f32 v[184:185], v[184:185], v[140:141]
	v_pk_mul_f32 v[182:183], v[182:183], v[138:139]
	v_pk_mul_f32 v[186:187], v[186:187], v[142:143]
	v_mul_f32_e32 v188, v184, v173
	v_mul_f32_e32 v192, v180, v173
	v_mul_f32_e32 v189, v185, v175
	v_mul_f32_e32 v193, v181, v175
	v_mul_f32_e32 v190, v186, v177
	v_mul_f32_e32 v194, v182, v177
	v_mul_f32_e32 v191, v187, v179
	v_mul_f32_e32 v195, v183, v179
	v_fma_f32 v188, v180, v172, -v188
	v_fma_f32 v192, v184, v172, v192
	v_fma_f32 v189, v181, v174, -v189
	v_fma_f32 v193, v185, v174, v193
	v_fma_f32 v190, v182, v176, -v190
	v_fma_f32 v194, v186, v176, v194
	v_fma_f32 v191, v183, v178, -v191
	v_fma_f32 v195, v187, v178, v195
	v_cvt_pk_bf16_f32 v188, v188, v189
	v_cvt_pk_bf16_f32 v189, v190, v191
	v_cvt_pk_bf16_f32 v190, v192, v193
	v_cvt_pk_bf16_f32 v191, v194, v195
	ds_write_b64 v204, v[188:189] offset:16976
	ds_write_b64 v204, v[190:191] offset:17104
	global_load_dwordx4 v[136:139], v170, s[58:59] offset:224
	global_load_dwordx4 v[140:143], v170, s[58:59] offset:480
	global_load_dwordx4 v[160:163], v201, s[8:9] offset:192
	global_load_dwordx4 v[164:167], v201, s[8:9] offset:208
	global_load_dwordx4 v[172:175], v203, s[8:9] offset:192
	global_load_dwordx4 v[176:179], v203, s[8:9] offset:208
	s_waitcnt vmcnt(6)
	v_pk_mul_f32 v[180:181], v[88:89], v[196:197]
	v_pk_mul_f32 v[184:185], v[72:73], v[196:197]
	v_pk_mul_f32 v[182:183], v[90:91], v[196:197]
	v_pk_mul_f32 v[186:187], v[74:75], v[196:197]
	v_pk_mul_f32 v[180:181], v[180:181], v[128:129]
	v_pk_mul_f32 v[184:185], v[184:185], v[132:133]
	v_pk_mul_f32 v[182:183], v[182:183], v[130:131]
	v_pk_mul_f32 v[186:187], v[186:187], v[134:135]
	v_mul_f32_e32 v188, v184, v145
	v_mul_f32_e32 v192, v180, v145
	v_mul_f32_e32 v189, v185, v147
	v_mul_f32_e32 v193, v181, v147
	v_mul_f32_e32 v190, v186, v149
	v_mul_f32_e32 v194, v182, v149
	v_mul_f32_e32 v191, v187, v151
	v_mul_f32_e32 v195, v183, v151
	v_fma_f32 v188, v180, v144, -v188
	v_fma_f32 v192, v184, v144, v192
	v_fma_f32 v189, v181, v146, -v189
	v_fma_f32 v193, v185, v146, v193
	v_fma_f32 v190, v182, v148, -v190
	v_fma_f32 v194, v186, v148, v194
	v_fma_f32 v191, v183, v150, -v191
	v_fma_f32 v195, v187, v150, v195
	v_cvt_pk_bf16_f32 v188, v188, v189
	v_cvt_pk_bf16_f32 v189, v190, v191
	v_cvt_pk_bf16_f32 v190, v192, v193
	v_cvt_pk_bf16_f32 v191, v194, v195
	ds_write_b64 v204, v[188:189] offset:96
	ds_write_b64 v204, v[190:191] offset:224
	v_pk_mul_f32 v[180:181], v[24:25], v[198:199]
	v_pk_mul_f32 v[184:185], v[8:9], v[198:199]
	v_pk_mul_f32 v[182:183], v[26:27], v[198:199]
	v_pk_mul_f32 v[186:187], v[10:11], v[198:199]
	v_pk_mul_f32 v[180:181], v[180:181], v[128:129]
	v_pk_mul_f32 v[184:185], v[184:185], v[132:133]
	v_pk_mul_f32 v[182:183], v[182:183], v[130:131]
	v_pk_mul_f32 v[186:187], v[186:187], v[134:135]
	v_mul_f32_e32 v188, v184, v153
	v_mul_f32_e32 v192, v180, v153
	v_mul_f32_e32 v189, v185, v155
	v_mul_f32_e32 v193, v181, v155
	v_mul_f32_e32 v190, v186, v157
	v_mul_f32_e32 v194, v182, v157
	v_mul_f32_e32 v191, v187, v159
	v_mul_f32_e32 v195, v183, v159
	v_fma_f32 v188, v180, v152, -v188
	v_fma_f32 v192, v184, v152, v192
	v_fma_f32 v189, v181, v154, -v189
	v_fma_f32 v193, v185, v154, v193
	v_fma_f32 v190, v182, v156, -v190
	v_fma_f32 v194, v186, v156, v194
	v_fma_f32 v191, v183, v158, -v191
	v_fma_f32 v195, v187, v158, v195
	v_cvt_pk_bf16_f32 v188, v188, v189
	v_cvt_pk_bf16_f32 v189, v190, v191
	v_cvt_pk_bf16_f32 v190, v192, v193
	v_cvt_pk_bf16_f32 v191, v194, v195
	ds_write_b64 v204, v[188:189] offset:16992
	ds_write_b64 v204, v[190:191] offset:17120
	s_waitcnt vmcnt(0)
	v_pk_mul_f32 v[180:181], v[92:93], v[196:197]
	v_pk_mul_f32 v[184:185], v[76:77], v[196:197]
	v_pk_mul_f32 v[182:183], v[94:95], v[196:197]
	v_pk_mul_f32 v[186:187], v[78:79], v[196:197]
	v_pk_mul_f32 v[180:181], v[180:181], v[136:137]
	v_pk_mul_f32 v[184:185], v[184:185], v[140:141]
	v_pk_mul_f32 v[182:183], v[182:183], v[138:139]
	v_pk_mul_f32 v[186:187], v[186:187], v[142:143]
	v_mul_f32_e32 v188, v184, v161
	v_mul_f32_e32 v192, v180, v161
	v_mul_f32_e32 v189, v185, v163
	v_mul_f32_e32 v193, v181, v163
	v_mul_f32_e32 v190, v186, v165
	v_mul_f32_e32 v194, v182, v165
	v_mul_f32_e32 v191, v187, v167
	v_mul_f32_e32 v195, v183, v167
	v_fma_f32 v188, v180, v160, -v188
	v_fma_f32 v192, v184, v160, v192
	v_fma_f32 v189, v181, v162, -v189
	v_fma_f32 v193, v185, v162, v193
	v_fma_f32 v190, v182, v164, -v190
	v_fma_f32 v194, v186, v164, v194
	v_fma_f32 v191, v183, v166, -v191
	v_fma_f32 v195, v187, v166, v195
	v_cvt_pk_bf16_f32 v188, v188, v189
	v_cvt_pk_bf16_f32 v189, v190, v191
	v_cvt_pk_bf16_f32 v190, v192, v193
	v_cvt_pk_bf16_f32 v191, v194, v195
	ds_write_b64 v204, v[188:189] offset:112
	ds_write_b64 v204, v[190:191] offset:240
	v_pk_mul_f32 v[180:181], v[28:29], v[198:199]
	v_pk_mul_f32 v[184:185], v[12:13], v[198:199]
	v_pk_mul_f32 v[182:183], v[30:31], v[198:199]
	v_pk_mul_f32 v[186:187], v[14:15], v[198:199]
	v_pk_mul_f32 v[180:181], v[180:181], v[136:137]
	v_pk_mul_f32 v[184:185], v[184:185], v[140:141]
	v_pk_mul_f32 v[182:183], v[182:183], v[138:139]
	v_pk_mul_f32 v[186:187], v[186:187], v[142:143]
	v_mul_f32_e32 v188, v184, v173
	v_mul_f32_e32 v192, v180, v173
	v_mul_f32_e32 v189, v185, v175
	v_mul_f32_e32 v193, v181, v175
	v_mul_f32_e32 v190, v186, v177
	v_mul_f32_e32 v194, v182, v177
	v_mul_f32_e32 v191, v187, v179
	v_mul_f32_e32 v195, v183, v179
	v_fma_f32 v188, v180, v172, -v188
	v_fma_f32 v192, v184, v172, v192
	v_fma_f32 v189, v181, v174, -v189
	v_fma_f32 v193, v185, v174, v193
	v_fma_f32 v190, v182, v176, -v190
	v_fma_f32 v194, v186, v176, v194
	v_fma_f32 v191, v183, v178, -v191
	v_fma_f32 v195, v187, v178, v195
	v_cvt_pk_bf16_f32 v188, v188, v189
	v_cvt_pk_bf16_f32 v189, v190, v191
	v_cvt_pk_bf16_f32 v190, v192, v193
	v_cvt_pk_bf16_f32 v191, v194, v195
	ds_write_b64 v204, v[188:189] offset:17008
	ds_write_b64 v204, v[190:191] offset:17136
	s_branch .Lqk2_flush

.Lqk2_k:
	s_cmp_lg_u32 s26, 0
	s_cbranch_scc1 .Lqk2_kc
	s_mul_i32 s55, s35, 0x900
	s_add_u32 s55, s55, s12
	s_add_u32 s55, s55, 0x100
	s_branch .Lqk2_kd
